# layer-0 only: 1024 more layer-1 items converted in the FFN-up idle half round instead of the (longest) layer-0 FFN-down tail
# speedup vs baseline: 1.0047x; 1.0047x over previous
; __device__ __forceinline__ PItem p0_decode(const Args& a, int it) {
;     constexpr int I_IN = 16 * 96, I_OUT = 16 * 32, I_W1 = 16 * 88, I_W2 = 44 * 32, I_LAYER = I_IN + I_OUT + 2 * I_W1 + I_W2;
;     const int l = it / I_LAYER, e = l >> 1, odd = l & 1; int r = it % I_LAYER;
;     unsigned char* wl = a.ws + WS_W + (size_t)l * W_LAYER; float* cv = (float*)(a.ws + WS_CVEC) + (size_t)l * CVEC_LAYER;
;     PItem p;
;     if (r < I_IN) { const int kb = r / 96, nb = r % 96; p.W = (odd ? a.in[13] : a.in[5]) + (size_t)e * D * EIN; p.N = EIN; p.K = D; p.g = l > 0 ? a.in[21] + (size_t)(l - 1) * D : nullptr; p.be = l > 0 ? a.in[22] + (size_t)(l - 1) * D : nullptr;
;         p.WT = (bf16*)(wl + W_IN); p.drow0 = in_dst_row(32 * nb, odd); p.k0 = 64 * kb; p.n0 = 32 * nb; p.c1 = cv; p.c2 = cv + EIN; return p; } r -= I_IN;
;     if (r < I_OUT) { const int kb = r / 32, nb = r % 32; p.W = (odd ? a.in[15] : a.in[6]) + (size_t)e * D * D; p.N = D; p.K = D; p.g = nullptr; p.be = nullptr;
;         p.WT = (bf16*)(wl + W_OUT); p.drow0 = 32 * nb; p.k0 = 64 * kb; p.n0 = 32 * nb; p.c1 = nullptr; p.c2 = nullptr; return p; } r -= I_OUT;
;     if (r < 2 * I_W1) { const int second = r >= I_W1; if (second) r -= I_W1; const int kb = r / 88, nb = r % 88, n0 = 32 * nb; p.W = (second ? a.in[17] : a.in[16]) + (size_t)l * D * DFF; p.N = DFF; p.K = D;
;         p.g = a.in[19] + (size_t)l * D; p.be = a.in[20] + (size_t)l * D; p.WT = (bf16*)(wl + W_13); p.drow0 = 256 * (n0 >> 7) + (second ? 128 : 0) + (n0 & 127); p.k0 = 64 * kb; p.n0 = n0; p.c1 = cv + 2 * EIN; p.c2 = cv + 2 * EIN + NUP; return p; } r -= 2 * I_W1;
; __global__ void __launch_bounds__(NWAVES * 64, 2) mk_fwd(Args args) {
;     ...
;             if (F.G == 256 && (int)blockIdx.x >= 128) { const int wi = (int)blockIdx.x - 128;
;                 if (l == 0) p_convert_tail(F, args, P_ILAYER - P_IW2, P_ILAYER, wi, 128);
;                 if (l < 3) { const int xs = (l == 0) ? 768 : 1792; p_convert_tail(F, args, (l + 2) * P_ILAYER - xs, (l + 2) * P_ILAYER, wi, 128); } }
.LBB0_1294:
	v_readlane_b32 s0, v255, 62
	s_cmp_eq_u32 s0, 3
	v_readlane_b32 s1, v255, 63
	s_cbranch_scc1 .LBB0_1348
	v_readlane_b32 s0, v255, 53
	v_readlane_b32 s1, v255, 54
	s_and_b64 s[0:1], s[0:1], exec
	v_readlane_b32 s10, v255, 62
	s_movk_i32 s0, 0xf700
	s_mul_i32 s7, s10, 0x1880
	s_cselect_b32 s0, s0, 0xfffff500
	s_addk_i32 s7, 0x3100
	v_readlane_b32 s1, v253, 59
	s_add_i32 s1, s1, s7
	v_mbcnt_lo_u32_b32 v0, -1, 0
	v_mbcnt_hi_u32_b32 v0, -1, v0
	s_add_i32 s13, s1, s0
	v_add_u32_e32 v0, s75, v0
	s_cmp_ge_i32 s13, s7
	v_readlane_b32 s11, v255, 63
	s_cbranch_scc1 .LBB0_1348
	s_mul_hi_i32 s0, s13, 0x5397829d
	s_lshr_b32 s1, s0, 31
	s_ashr_i32 s0, s0, 11
	s_add_i32 s30, s0, s1
	s_mul_i32 s1, s30, 0x1880
	s_ashr_i32 s34, s30, 1
	s_and_b32 s0, s30, 1
	s_sub_i32 s1, s13, s1
	s_ashr_i32 s31, s30, 31
	s_mul_i32 s10, s30, 0x1880000
	v_readlane_b32 s11, v253, 5
	s_mul_hi_i32 s2, s30, 0x1880000
	s_add_u32 s22, s11, s10
	v_readlane_b32 s10, v253, 6
	s_addc_u32 s23, s10, s2
	s_mul_i32 s10, s30, 0x11000
	v_readlane_b32 s11, v253, 7
	s_mul_hi_i32 s2, s30, 0x11000
	s_add_u32 s26, s11, s10
	v_readlane_b32 s10, v253, 8
	s_addc_u32 s27, s10, s2
	s_cmpk_gt_i32 s1, 0x5ff
	s_mov_b64 s[48:49], -1
	s_cbranch_scc0 .LBB0_1305
	s_cmpk_gt_u32 s1, 0x7ff
	s_cbranch_scc0 .LBB0_1302
	s_mov_b64 s[18:19], -1
	s_cmpk_gt_u32 s1, 0x12ff
	s_mul_hi_i32 s2, s30, 0xb00000
	s_mul_i32 s17, s30, 0xb00000
	s_cbranch_scc0 .LBB0_1300
	v_readlane_b32 s56, v253, 26
	v_readlane_b32 s57, v253, 27
	s_add_u32 s10, s56, s17
	s_addc_u32 s11, s57, s2
	s_add_u32 s14, s22, 0x1300000
	s_addc_u32 s15, s23, 0
	s_lshl_b32 s16, s1, 1
	s_lshl_b32 s12, s1, 5
	s_and_b32 s16, s16, 0x7fffffc0
	v_readlane_b32 s58, v253, 28
	v_readlane_b32 s59, v253, 29
	v_readlane_b32 s60, v253, 30
	v_readlane_b32 s61, v253, 31
	v_readlane_b32 s62, v253, 32
	v_readlane_b32 s63, v253, 33
	s_and_b32 s12, s12, 0x3e0
	s_addk_i32 s16, 0xda00
	s_mov_b64 s[18:19], 0

; __device__ __forceinline__ PItem p0_decode(const Args& a, int it) {
;     constexpr int I_IN = 16 * 96, I_OUT = 16 * 32, I_W1 = 16 * 88, I_W2 = 44 * 32, I_LAYER = I_IN + I_OUT + 2 * I_W1 + I_W2;
;     const int l = it / I_LAYER, e = l >> 1, odd = l & 1; int r = it % I_LAYER;
;     unsigned char* wl = a.ws + WS_W + (size_t)l * W_LAYER; float* cv = (float*)(a.ws + WS_CVEC) + (size_t)l * CVEC_LAYER;
;     PItem p;
;     if (r < I_IN) { const int kb = r / 96, nb = r % 96; p.W = (odd ? a.in[13] : a.in[5]) + (size_t)e * D * EIN; p.N = EIN; p.K = D; p.g = l > 0 ? a.in[21] + (size_t)(l - 1) * D : nullptr; p.be = l > 0 ? a.in[22] + (size_t)(l - 1) * D : nullptr;
;         p.WT = (bf16*)(wl + W_IN); p.drow0 = in_dst_row(32 * nb, odd); p.k0 = 64 * kb; p.n0 = 32 * nb; p.c1 = cv; p.c2 = cv + EIN; return p; } r -= I_IN;
;     if (r < I_OUT) { const int kb = r / 32, nb = r % 32; p.W = (odd ? a.in[15] : a.in[6]) + (size_t)e * D * D; p.N = D; p.K = D; p.g = nullptr; p.be = nullptr;
;         p.WT = (bf16*)(wl + W_OUT); p.drow0 = 32 * nb; p.k0 = 64 * kb; p.n0 = 32 * nb; p.c1 = nullptr; p.c2 = nullptr; return p; } r -= I_OUT;
;     if (r < 2 * I_W1) { const int second = r >= I_W1; if (second) r -= I_W1; const int kb = r / 88, nb = r % 88, n0 = 32 * nb; p.W = (second ? a.in[17] : a.in[16]) + (size_t)l * D * DFF; p.N = DFF; p.K = D;
; __global__ void __launch_bounds__(NWAVES * 64, 2) mk_fwd(Args args) {
;     ...
;                 { int Gq = F.G; asm volatile("" : "+s"(Gq)); const int nmu = g.N >> 5, mfirst = (nmu <= Gq / 2 || Gq < 256) ? (Gq - nmu > 0 ? Gq - nmu : 0) : Gq / 2; for (int mu = (int)blockIdx.x - mfirst; mu >= 0 && mu < nmu; mu += Gq - mfirst) pg8::mini_ring(F.lds + RING_OFF, g.A, g.Bt, g.K, E, mu, F.wave);
;                   if (l < 3) { if (mfirst > 0) { if ((int)blockIdx.x < mfirst) { p_convert_tail(F, args, (l + 1) * P_ILAYER, (l + 2) * P_ILAYER - ((F.G == 256) ? (l == 0 ? 768 : 1792) : 0), (int)blockIdx.x, mfirst); if (l == 0) p_state_copies_tail(F, args, (int)blockIdx.x, mfirst); } }
;                   else { p_convert_tail(F, args, (l + 1) * P_ILAYER, (l + 2) * P_ILAYER - ((F.G == 256) ? (l == 0 ? 768 : 1792) : 0), (int)blockIdx.x, F.G); if (l == 0) p_state_copies_tail(F, args, (int)blockIdx.x, F.G); } } } }
.LBB0_1546:
	s_waitcnt vmcnt(24)
	s_barrier
	v_readlane_b32 s0, v255, 62
	s_cmp_lg_u32 s0, 3
	s_mov_b64 s[10:11], -1
	v_readlane_b32 s1, v255, 63
	s_cmp_lt_i32 s29, 33
	s_cbranch_scc0 .LBB0_1627
	v_readlane_b32 s0, v255, 62
	v_readlane_b32 s1, v255, 63
	s_mul_i32 s2, s0, 0x1880
	v_readlane_b32 s0, v255, 53
	v_readlane_b32 s1, v255, 54
	s_and_b64 s[0:1], s[0:1], exec
	s_movk_i32 s0, 0xf700
	s_cselect_b32 s7, s0, 0xfffff500
	v_readlane_b32 s0, v252, 62
	v_readlane_b32 s1, v252, 63
	s_and_b64 s[0:1], s[0:1], exec
	s_cselect_b32 s0, s7, 0
	s_add_i32 s7, s2, s0
	v_readlane_b32 s0, v253, 60
	s_addk_i32 s7, 0x3100
	v_mbcnt_lo_u32_b32 v0, -1, 0
	v_mbcnt_hi_u32_b32 v0, -1, v0
	s_add_i32 s29, s0, s2
	v_add_u32_e32 v0, s75, v0
	s_cmp_ge_i32 s29, s7
	s_cbranch_scc1 .LBB0_1601
	s_mul_hi_i32 s0, s29, 0x5397829d
	s_lshr_b32 s1, s0, 31
	s_ashr_i32 s0, s0, 11
	s_add_i32 s26, s0, s1
	s_mul_i32 s1, s26, 0x1880
	s_ashr_i32 s30, s26, 1
	s_and_b32 s0, s26, 1
	s_sub_i32 s1, s29, s1
	s_ashr_i32 s27, s26, 31
	s_mul_i32 s10, s26, 0x1880000
	v_readlane_b32 s11, v253, 5
	s_mul_hi_i32 s2, s26, 0x1880000
	s_add_u32 s22, s11, s10
	v_readlane_b32 s10, v253, 6
	s_addc_u32 s23, s10, s2
	s_mul_i32 s10, s26, 0x11000
	v_readlane_b32 s11, v253, 7
	s_mul_hi_i32 s2, s26, 0x11000
	s_add_u32 s24, s11, s10
	v_readlane_b32 s10, v253, 8
	s_addc_u32 s25, s10, s2
	s_cmpk_gt_i32 s1, 0x5ff
	s_mov_b64 s[46:47], -1
	s_cbranch_scc0 .LBB0_1558
	s_cmpk_gt_u32 s1, 0x7ff
	s_cbranch_scc0 .LBB0_1555
	s_mov_b64 s[18:19], -1
	s_cmpk_gt_u32 s1, 0x12ff
	s_mul_hi_i32 s2, s26, 0xb00000
	s_mul_i32 s13, s26, 0xb00000
	s_cbranch_scc0 .LBB0_1553
	v_readlane_b32 s56, v253, 26
	v_readlane_b32 s57, v253, 27
	s_add_u32 s10, s56, s13
	s_addc_u32 s11, s57, s2
	s_add_u32 s14, s22, 0x1300000
	s_addc_u32 s15, s23, 0
	s_lshl_b32 s16, s1, 1
	s_lshl_b32 s12, s1, 5
	s_and_b32 s16, s16, 0x7fffffc0
	v_readlane_b32 s58, v253, 28
	v_readlane_b32 s59, v253, 29
	v_readlane_b32 s60, v253, 30
	v_readlane_b32 s61, v253, 31
	v_readlane_b32 s62, v253, 32
	v_readlane_b32 s63, v253, 33
	s_and_b32 s12, s12, 0x3e0
	s_addk_i32 s16, 0xda00
	s_mov_b64 s[18:19], 0

; __device__ __forceinline__ PItem p0_decode(const Args& a, int it) {
;     constexpr int I_IN = 16 * 96, I_OUT = 16 * 32, I_W1 = 16 * 88, I_W2 = 44 * 32, I_LAYER = I_IN + I_OUT + 2 * I_W1 + I_W2;
;     const int l = it / I_LAYER, e = l >> 1, odd = l & 1; int r = it % I_LAYER;
;     unsigned char* wl = a.ws + WS_W + (size_t)l * W_LAYER; float* cv = (float*)(a.ws + WS_CVEC) + (size_t)l * CVEC_LAYER;
;     PItem p;
;     if (r < I_IN) { const int kb = r / 96, nb = r % 96; p.W = (odd ? a.in[13] : a.in[5]) + (size_t)e * D * EIN; p.N = EIN; p.K = D; p.g = l > 0 ? a.in[21] + (size_t)(l - 1) * D : nullptr; p.be = l > 0 ? a.in[22] + (size_t)(l - 1) * D : nullptr;
;         p.WT = (bf16*)(wl + W_IN); p.drow0 = in_dst_row(32 * nb, odd); p.k0 = 64 * kb; p.n0 = 32 * nb; p.c1 = cv; p.c2 = cv + EIN; return p; } r -= I_IN;
;     if (r < I_OUT) { const int kb = r / 32, nb = r % 32; p.W = (odd ? a.in[15] : a.in[6]) + (size_t)e * D * D; p.N = D; p.K = D; p.g = nullptr; p.be = nullptr;
;         p.WT = (bf16*)(wl + W_OUT); p.drow0 = 32 * nb; p.k0 = 64 * kb; p.n0 = 32 * nb; p.c1 = nullptr; p.c2 = nullptr; return p; } r -= I_OUT;
;     if (r < 2 * I_W1) { const int second = r >= I_W1; if (second) r -= I_W1; const int kb = r / 88, nb = r % 88, n0 = 32 * nb; p.W = (second ? a.in[17] : a.in[16]) + (size_t)l * D * DFF; p.N = DFF; p.K = D;
; __global__ void __launch_bounds__(NWAVES * 64, 2) mk_fwd(Args args) {
;     ...
;                 { int Gq = F.G; asm volatile("" : "+s"(Gq)); const int nmu = g.N >> 5, mfirst = (nmu <= Gq / 2 || Gq < 256) ? (Gq - nmu > 0 ? Gq - nmu : 0) : Gq / 2; for (int mu = (int)blockIdx.x - mfirst; mu >= 0 && mu < nmu; mu += Gq - mfirst) pg8::mini_ring(F.lds + RING_OFF, g.A, g.Bt, g.K, E, mu, F.wave);
;                   if (l < 3) { if (mfirst > 0) { if ((int)blockIdx.x < mfirst) { p_convert_tail(F, args, (l + 1) * P_ILAYER, (l + 2) * P_ILAYER - ((F.G == 256) ? (l == 0 ? 768 : 1792) : 0), (int)blockIdx.x, mfirst); if (l == 0) p_state_copies_tail(F, args, (int)blockIdx.x, mfirst); } }
;                   else { p_convert_tail(F, args, (l + 1) * P_ILAYER, (l + 2) * P_ILAYER - ((F.G == 256) ? (l == 0 ? 768 : 1792) : 0), (int)blockIdx.x, F.G); if (l == 0) p_state_copies_tail(F, args, (int)blockIdx.x, F.G); } } } }
.LBB0_1627:
	s_and_b64 vcc, exec, s[10:11]
	s_cbranch_vccz .LBB0_1707
	v_readlane_b32 s0, v254, 27
	s_cmp_ge_i32 s0, s28
	v_readlane_b32 s1, v254, 28
	s_cbranch_scc1 .LBB0_1707
	v_readlane_b32 s0, v255, 62
	s_cmp_eq_u32 s0, 3
	s_cbranch_scc1 .LBB0_1682
	v_readlane_b32 s0, v255, 62
	v_readlane_b32 s1, v255, 63
	s_mul_i32 s2, s0, 0x1880
	v_readlane_b32 s0, v255, 53
	v_readlane_b32 s1, v255, 54
	s_and_b64 s[0:1], s[0:1], exec
	s_movk_i32 s0, 0xf700
	s_cselect_b32 s7, s0, 0xfffff500
	v_readlane_b32 s0, v252, 62
	v_readlane_b32 s1, v252, 63
	s_and_b64 s[0:1], s[0:1], exec
	s_cselect_b32 s0, s7, 0
	s_add_i32 s7, s2, s0
	v_readlane_b32 s0, v253, 60
	s_addk_i32 s7, 0x3100
	v_mbcnt_lo_u32_b32 v0, -1, 0
	v_mbcnt_hi_u32_b32 v0, -1, v0
	s_add_i32 s29, s0, s2
	v_add_u32_e32 v0, s75, v0
	s_cmp_ge_i32 s29, s7
	s_cbranch_scc1 .LBB0_1682
	s_mul_hi_i32 s0, s29, 0x5397829d
	s_lshr_b32 s1, s0, 31
	s_ashr_i32 s0, s0, 11
	s_add_i32 s26, s0, s1
	s_mul_i32 s1, s26, 0x1880
	s_ashr_i32 s30, s26, 1
	s_and_b32 s0, s26, 1
	s_sub_i32 s1, s29, s1
	s_ashr_i32 s27, s26, 31
	s_mul_i32 s10, s26, 0x1880000
	v_readlane_b32 s11, v253, 5
	s_mul_hi_i32 s2, s26, 0x1880000
	s_add_u32 s22, s11, s10
	v_readlane_b32 s10, v253, 6
	s_addc_u32 s23, s10, s2
	s_mul_i32 s10, s26, 0x11000
	v_readlane_b32 s11, v253, 7
	s_mul_hi_i32 s2, s26, 0x11000
	s_add_u32 s24, s11, s10
	v_readlane_b32 s10, v253, 8
	s_addc_u32 s25, s10, s2
	v_readlane_b32 s48, v250, 0
	s_cmpk_gt_i32 s1, 0x5ff
	s_mov_b64 s[46:47], -1
	v_readlane_b32 s49, v250, 1
	s_cbranch_scc0 .LBB0_1639
	s_cmpk_gt_u32 s1, 0x7ff
	s_cbranch_scc0 .LBB0_1636
	s_mov_b64 s[18:19], -1
	s_cmpk_gt_u32 s1, 0x12ff
	s_mul_hi_i32 s2, s26, 0xb00000
	s_mul_i32 s13, s26, 0xb00000
	s_cbranch_scc0 .LBB0_1634
	v_readlane_b32 s56, v253, 26
	v_readlane_b32 s57, v253, 27
	s_add_u32 s10, s56, s13
	s_addc_u32 s11, s57, s2
	s_add_u32 s14, s22, 0x1300000
	s_addc_u32 s15, s23, 0
	s_lshl_b32 s16, s1, 1
	s_lshl_b32 s12, s1, 5
	s_and_b32 s16, s16, 0x7fffffc0
	v_readlane_b32 s58, v253, 28
	v_readlane_b32 s59, v253, 29
	v_readlane_b32 s60, v253, 30
	v_readlane_b32 s61, v253, 31
	v_readlane_b32 s62, v253, 32
	v_readlane_b32 s63, v253, 33
	s_and_b32 s12, s12, 0x3e0
	s_addk_i32 s16, 0xda00
	s_mov_b64 s[18:19], 0
